# hot loop heads pinned to 64-byte alignment (GEMM K-loops at +44 bytes)
# baseline (speedup 1.0000x reference)
.LBB0_85:
	v_add3_u32 v238, v232, v233, v236
	v_add3_u32 v239, v234, v233, v237
	v_add3_u32 v236, v232, v235, v236
	v_add3_u32 v237, v234, v235, v237
	v_add_u32_e32 v236, 0x10000, v236
	v_add_u32_e32 v237, 0x10000, v237
	v_add_u32_e32 v254, 0x8000, v229
	v_add_u32_e32 v255, 0x8000, v230
	ds_read_b128 v[164:167], v238
	ds_read_b128 v[168:171], v238 offset:256
	ds_read_b128 v[172:175], v238 offset:512
	ds_read_b128 v[192:195], v238 offset:768
	ds_read_b128 v[176:179], v236
	ds_read_b128 v[180:183], v236 offset:256
	ds_read_b128 v[184:187], v236 offset:512
	ds_read_b128 v[188:191], v236 offset:768
	ds_read_b128 v[196:199], v238 offset:1024
	ds_read_b128 v[200:203], v238 offset:1280
	ds_read_b128 v[204:207], v238 offset:1536
	ds_read_b128 v[208:211], v238 offset:1792
	s_nop 0
	v_xor_b32_e32 v238, 0x8000, v238
	v_xor_b32_e32 v236, 0x8000, v236
	.p2align 6
	s_nop 0
	s_nop 0
	s_nop 0
	s_nop 0
	s_nop 0
	s_nop 0
	s_nop 0
	s_nop 0
	s_nop 0
	s_nop 0
	s_nop 0

.LBB0_243:
	s_cmp_lt_i32 s42, 1
	s_waitcnt lgkmcnt(0)
	s_barrier
	s_cbranch_scc1 .LBB0_250
	v_bfe_u32 v4, v12, 4, 2
	v_ashrrev_i32_e32 v6, 1, v12
	v_lshrrev_b32_e32 v3, 4, v12
	v_and_b32_e32 v5, 15, v12
	v_and_b32_e32 v7, 0xffffffc0, v6
	v_or_b32_e32 v6, 4, v4
	v_and_b32_e32 v2, 64, v12
	v_lshlrev_b32_e32 v128, 12, v4
	v_bitop3_b32 v3, v3, v5, 3 bitop3:0x6c
	v_lshlrev_b32_e32 v129, 12, v6
	v_bitop3_b32 v5, v4, v5, 4 bitop3:0x36
	v_lshlrev_b32_e32 v130, 11, v4
	v_lshlrev_b32_e32 v131, 11, v6
	v_add_u32_e32 v4, v13, v10
	v_mov_b32_e32 v6, 0
	v_add_lshl_u32 v132, v4, v11, 10
	s_mov_b32 s43, 0
	v_lshlrev_b32_e32 v133, 4, v7
	v_lshlrev_b32_e32 v134, 4, v2
	v_lshlrev_b32_e32 v135, 4, v3
	v_lshlrev_b32_e32 v136, 4, v5
	v_mov_b32_e32 v7, v6
	v_mov_b32_e32 v8, v6
	v_mov_b32_e32 v9, v6
	v_mov_b32_e32 v2, v6
	v_mov_b32_e32 v3, v6
	v_mov_b32_e32 v4, v6
	v_mov_b32_e32 v5, v6
	v_mov_b32_e32 v10, v6
	v_mov_b32_e32 v11, v6
	v_mov_b32_e32 v12, v6
	v_mov_b32_e32 v13, v6
	v_mov_b32_e32 v14, v6
	v_mov_b32_e32 v15, v6
	v_mov_b32_e32 v16, v6
	v_mov_b32_e32 v17, v6
	v_mov_b32_e32 v18, v6
	v_mov_b32_e32 v19, v6
	v_mov_b32_e32 v20, v6
	v_mov_b32_e32 v21, v6
	v_mov_b32_e32 v22, v6
	v_mov_b32_e32 v23, v6
	v_mov_b32_e32 v24, v6
	v_mov_b32_e32 v25, v6
	v_mov_b32_e32 v26, v6
	v_mov_b32_e32 v27, v6
	v_mov_b32_e32 v28, v6
	v_mov_b32_e32 v29, v6
	v_mov_b32_e32 v30, v6
	v_mov_b32_e32 v31, v6
	v_mov_b32_e32 v32, v6
	v_mov_b32_e32 v33, v6
	v_mov_b32_e32 v44, v6
	v_mov_b32_e32 v45, v6
	v_mov_b32_e32 v46, v6
	v_mov_b32_e32 v47, v6
	v_mov_b32_e32 v48, v6
	v_mov_b32_e32 v49, v6
	v_mov_b32_e32 v50, v6
	v_mov_b32_e32 v51, v6
	v_mov_b32_e32 v60, v6
	v_mov_b32_e32 v61, v6
	v_mov_b32_e32 v62, v6
	v_mov_b32_e32 v63, v6
	v_mov_b32_e32 v64, v6
	v_mov_b32_e32 v65, v6
	v_mov_b32_e32 v66, v6
	v_mov_b32_e32 v67, v6
	v_mov_b32_e32 v72, v6
	v_mov_b32_e32 v73, v6
	v_mov_b32_e32 v74, v6
	v_mov_b32_e32 v75, v6
	v_mov_b32_e32 v80, v6
	v_mov_b32_e32 v81, v6
	v_mov_b32_e32 v82, v6
	v_mov_b32_e32 v83, v6
	v_mov_b32_e32 v92, v6
	v_mov_b32_e32 v93, v6
	v_mov_b32_e32 v94, v6
	v_mov_b32_e32 v95, v6
	v_mov_b32_e32 v96, v6
	v_mov_b32_e32 v97, v6
	v_mov_b32_e32 v98, v6
	v_mov_b32_e32 v99, v6
	.p2align 6

.LBB0_253:
	s_cmp_lt_i32 s24, 1
	s_waitcnt lgkmcnt(0)
	s_barrier
	s_cbranch_scc1 .LBB0_260
	v_bfe_u32 v70, v86, 4, 2
	v_ashrrev_i32_e32 v76, 1, v86
	v_lshrrev_b32_e32 v69, 4, v86
	v_and_b32_e32 v71, 15, v86
	v_and_b32_e32 v77, 0xffffffc0, v76
	v_or_b32_e32 v76, 4, v70
	v_and_b32_e32 v68, 64, v86
	v_lshlrev_b32_e32 v226, 12, v70
	v_bitop3_b32 v69, v69, v71, 3 bitop3:0x6c
	v_lshlrev_b32_e32 v227, 12, v76
	v_bitop3_b32 v71, v70, v71, 4 bitop3:0x36
	v_lshlrev_b32_e32 v228, 11, v70
	v_lshlrev_b32_e32 v229, 11, v76
	v_add_u32_e32 v70, v87, v84
	v_mov_b32_e32 v76, 0
	v_add_lshl_u32 v230, v70, v85, 9
	s_mov_b32 s59, 0
	v_lshlrev_b32_e32 v231, 4, v77
	v_lshlrev_b32_e32 v232, 4, v68
	v_lshlrev_b32_e32 v233, 4, v69
	v_lshlrev_b32_e32 v234, 4, v71
	v_mov_b32_e32 v77, v76
	v_mov_b32_e32 v78, v76
	v_mov_b32_e32 v79, v76
	v_mov_b32_e32 v68, v76
	v_mov_b32_e32 v69, v76
	v_mov_b32_e32 v70, v76
	v_mov_b32_e32 v71, v76
	v_mov_b32_e32 v84, v76
	v_mov_b32_e32 v85, v76
	v_mov_b32_e32 v86, v76
	v_mov_b32_e32 v87, v76
	v_mov_b32_e32 v88, v76
	v_mov_b32_e32 v89, v76
	v_mov_b32_e32 v90, v76
	v_mov_b32_e32 v91, v76
	v_mov_b32_e32 v100, v76
	v_mov_b32_e32 v101, v76
	v_mov_b32_e32 v102, v76
	v_mov_b32_e32 v103, v76
	v_mov_b32_e32 v104, v76
	v_mov_b32_e32 v105, v76
	v_mov_b32_e32 v106, v76
	v_mov_b32_e32 v107, v76
	v_mov_b32_e32 v108, v76
	v_mov_b32_e32 v109, v76
	v_mov_b32_e32 v110, v76
	v_mov_b32_e32 v111, v76
	v_mov_b32_e32 v112, v76
	v_mov_b32_e32 v113, v76
	v_mov_b32_e32 v114, v76
	v_mov_b32_e32 v115, v76
	v_mov_b32_e32 v116, v76
	v_mov_b32_e32 v117, v76
	v_mov_b32_e32 v118, v76
	v_mov_b32_e32 v119, v76
	v_mov_b32_e32 v120, v76
	v_mov_b32_e32 v121, v76
	v_mov_b32_e32 v122, v76
	v_mov_b32_e32 v123, v76
	v_mov_b32_e32 v124, v76
	v_mov_b32_e32 v125, v76
	v_mov_b32_e32 v126, v76
	v_mov_b32_e32 v127, v76
	v_mov_b32_e32 v128, v76
	v_mov_b32_e32 v129, v76
	v_mov_b32_e32 v130, v76
	v_mov_b32_e32 v131, v76
	v_mov_b32_e32 v132, v76
	v_mov_b32_e32 v133, v76
	v_mov_b32_e32 v134, v76
	v_mov_b32_e32 v135, v76
	v_mov_b32_e32 v136, v76
	v_mov_b32_e32 v137, v76
	v_mov_b32_e32 v138, v76
	v_mov_b32_e32 v139, v76
	v_mov_b32_e32 v140, v76
	v_mov_b32_e32 v141, v76
	v_mov_b32_e32 v142, v76
	v_mov_b32_e32 v143, v76
	v_mov_b32_e32 v144, v76
	v_mov_b32_e32 v145, v76
	v_mov_b32_e32 v146, v76
	v_mov_b32_e32 v147, v76
	.p2align 6

.LBB0_304:
	s_or_b64 exec, exec, s[58:59]
	s_add_i32 s33, s97, 1
	s_add_i32 s76, s76, 4
	v_add_u32_e32 v184, 64, v184
	v_subrev_u32_e32 v183, 64, v183
	s_cmp_eq_u32 s97, s96
	s_mov_b32 s97, s33
	s_waitcnt lgkmcnt(0)
	s_barrier
	s_cbranch_scc1 .LBB0_301
	.p2align 6

.LBB0_364:
	s_andn2_saveexec_b64 s[58:59], s[82:83]
	s_cbranch_execz .LBB0_304
	s_cmp_eq_u32 s97, 0
	s_cbranch_scc1 .LBB0_304
	s_mov_b32 s33, 4
	s_cmp_lt_i32 s33, 1
	s_cbranch_scc1 .LBB0_304
	v_lshrrev_b32_e32 v246, 2, v217
	v_mul_u32_u24_e32 v246, 0x88, v246
	v_and_b32_e32 v247, 3, v217
	v_lshl_add_u32 v246, v247, 3, v246
	v_lshrrev_b32_e32 v247, 1, v1
	v_and_b32_e32 v247, 0x60, v247
	v_add_u32_e32 v247, v247, v246
	v_add_u32_e32 v247, 0x2600, v247
	v_add_u32_e32 v246, 0x1200, v246
	s_lshl_b32 s60, s76, 14
	s_and_b32 s60, s60, 0x10000
	s_add_i32 s60, s60, 0
	v_mov_b32_e32 v18, v183
	v_mov_b32_e32 v19, v184
	.p2align 6

.LBB0_391:
	s_cmp_lt_i32 s24, 1
	s_waitcnt lgkmcnt(0)
	s_barrier
	s_cbranch_scc1 .LBB0_398
	v_bfe_u32 v4, v10, 4, 2
	v_ashrrev_i32_e32 v6, 1, v10
	v_lshrrev_b32_e32 v3, 4, v10
	v_and_b32_e32 v5, 15, v10
	v_and_b32_e32 v7, 0xffffffc0, v6
	v_or_b32_e32 v6, 4, v4
	v_and_b32_e32 v2, 64, v10
	v_bitop3_b32 v3, v3, v5, 3 bitop3:0x6c
	v_lshlrev_b32_e32 v130, 12, v6
	v_bitop3_b32 v5, v4, v5, 4 bitop3:0x36
	v_lshlrev_b32_e32 v132, 11, v6
	v_add_u32_e32 v133, 0x80, v11
	v_mov_b32_e32 v6, 0
	v_lshlrev_b32_e32 v129, 12, v4
	v_lshlrev_b32_e32 v131, 11, v4
	v_add_u32_e32 v134, s54, v133
	s_mov_b32 s54, 0
	v_lshlrev_b32_e32 v135, 4, v7
	v_lshlrev_b32_e32 v136, 4, v2
	v_lshlrev_b32_e32 v137, 4, v3
	v_lshlrev_b32_e32 v138, 4, v5
	v_mov_b32_e32 v7, v6
	v_mov_b32_e32 v8, v6
	v_mov_b32_e32 v9, v6
	v_mov_b32_e32 v2, v6
	v_mov_b32_e32 v3, v6
	v_mov_b32_e32 v4, v6
	v_mov_b32_e32 v5, v6
	v_mov_b32_e32 v10, v6
	v_mov_b32_e32 v11, v6
	v_mov_b32_e32 v12, v6
	v_mov_b32_e32 v13, v6
	v_mov_b32_e32 v14, v6
	v_mov_b32_e32 v15, v6
	v_mov_b32_e32 v16, v6
	v_mov_b32_e32 v17, v6
	v_mov_b32_e32 v18, v6
	v_mov_b32_e32 v19, v6
	v_mov_b32_e32 v20, v6
	v_mov_b32_e32 v21, v6
	v_mov_b32_e32 v22, v6
	v_mov_b32_e32 v23, v6
	v_mov_b32_e32 v24, v6
	v_mov_b32_e32 v25, v6
	v_mov_b32_e32 v26, v6
	v_mov_b32_e32 v27, v6
	v_mov_b32_e32 v28, v6
	v_mov_b32_e32 v29, v6
	v_mov_b32_e32 v30, v6
	v_mov_b32_e32 v31, v6
	v_mov_b32_e32 v32, v6
	v_mov_b32_e32 v33, v6
	v_mov_b32_e32 v36, v6
	v_mov_b32_e32 v37, v6
	v_mov_b32_e32 v38, v6
	v_mov_b32_e32 v39, v6
	v_mov_b32_e32 v40, v6
	v_mov_b32_e32 v41, v6
	v_mov_b32_e32 v42, v6
	v_mov_b32_e32 v43, v6
	v_mov_b32_e32 v44, v6
	v_mov_b32_e32 v45, v6
	v_mov_b32_e32 v46, v6
	v_mov_b32_e32 v47, v6
	v_mov_b32_e32 v48, v6
	v_mov_b32_e32 v49, v6
	v_mov_b32_e32 v50, v6
	v_mov_b32_e32 v51, v6
	v_mov_b32_e32 v52, v6
	v_mov_b32_e32 v53, v6
	v_mov_b32_e32 v54, v6
	v_mov_b32_e32 v55, v6
	v_mov_b32_e32 v56, v6
	v_mov_b32_e32 v57, v6
	v_mov_b32_e32 v58, v6
	v_mov_b32_e32 v59, v6
	v_mov_b32_e32 v60, v6
	v_mov_b32_e32 v61, v6
	v_mov_b32_e32 v62, v6
	v_mov_b32_e32 v63, v6
	v_mov_b32_e32 v64, v6
	v_mov_b32_e32 v65, v6
	v_mov_b32_e32 v66, v6
	v_mov_b32_e32 v67, v6
	.p2align 6

.LBB0_675:
	s_or_b64 exec, exec, s[2:3]
	s_lshr_b32 s2, s24, 4
	s_lshl_b32 s3, s24, 5
	s_lshl_b32 s2, s2, 2
	s_and_b32 s31, s3, 0x7800
	s_or_b32 s3, s2, 0xf0
	v_mov_b32_e32 v2, s3
	s_or_b32 s2, s2, 0x1f0
	global_load_dword v186, v2, s[22:23]
	v_mov_b32_e32 v2, s2
	s_lshl_b32 s2, s24, 7
	s_and_b32 s2, s2, 0x780
	v_add_u32_e32 v188, s2, v154
	global_load_dword v187, v2, s[22:23]
	v_or_b32_e32 v2, v188, v151
	v_add_u32_e32 v2, s31, v2
	v_mov_b64_e32 v[4:5], s[28:29]
	v_mad_i64_i32 v[2:3], s[2:3], v2, s89, v[4:5]
	s_lshl_b32 s24, s30, 8
	v_lshl_add_u64 v[168:169], v[2:3], 0, s[24:25]
	v_mov_b32_e32 v165, v34
	v_lshl_add_u64 v[2:3], v[168:169], 0, v[164:165]
	global_load_dwordx4 v[36:39], v[2:3], off offset:1024
	global_load_dwordx4 v[40:43], v[2:3], off offset:1088
	global_load_dwordx4 v[44:47], v[2:3], off offset:1152
	global_load_dwordx4 v[48:51], v[2:3], off offset:1216
	v_add_u32_e32 v2, s31, v150
	v_mad_i64_i32 v[2:3], s[2:3], v2, s89, v[4:5]
	v_lshl_add_u64 v[2:3], v[2:3], 0, s[24:25]
	v_mov_b32_e32 v167, v34
	v_lshl_add_u64 v[20:21], v[2:3], 0, v[166:167]
	v_or_b32_e32 v2, s31, v148
	v_mad_u64_u32 v[4:5], s[2:3], v2, s89, v[4:5]
	s_mov_b32 s2, 0x3e000
	s_nop 0
	v_add_co_u32_e32 v8, vcc, s2, v20
	v_lshl_add_u64 v[4:5], v[4:5], 0, s[24:25]
	s_nop 0
	v_addc_co_u32_e32 v9, vcc, 0, v21, vcc
	v_lshl_add_u64 v[22:23], v[154:155], 1, v[4:5]
	global_load_dwordx4 v[4:7], v[20:21], off offset:2048
	s_nop 0
	global_load_dwordx4 v[8:11], v[8:9], off offset:2048
	s_nop 0
	global_load_dwordx4 v[12:15], v[22:23], off offset:3088
	global_load_dwordx4 v[16:19], v[22:23], off offset:3072
	s_mov_b32 s2, 0x7c000
	s_mov_b32 s30, 32
	s_waitcnt vmcnt(3)
	ds_write_b128 v178, v[4:7]
	s_waitcnt vmcnt(2)
	ds_write_b128 v178, v[8:11] offset:512
	s_waitcnt vmcnt(0)
	ds_write_b128 v226, v[16:19] offset:34816
	ds_write_b128 v226, v[12:15] offset:34832
	v_add_co_u32_e32 v4, vcc, s2, v20
	s_nop 1
	v_addc_co_u32_e32 v5, vcc, 0, v21, vcc
	global_load_dwordx4 v[72:75], v[4:5], off offset:2048
	v_add_co_u32_e32 v4, vcc, 0xba000, v20
	s_nop 1
	v_addc_co_u32_e32 v5, vcc, 0, v21, vcc
	global_load_dwordx4 v[80:83], v[4:5], off offset:2048
	v_add_co_u32_e32 v4, vcc, 0x7c000, v22
	s_nop 1
	v_addc_co_u32_e32 v5, vcc, 0, v23, vcc
	global_load_dwordx4 v[84:87], v[4:5], off offset:3072
	global_load_dwordx4 v[92:95], v[4:5], off offset:3088
	s_waitcnt lgkmcnt(0)
	s_barrier
	s_cmp_lt_i32 s30, 1
	s_cbranch_scc1 .LBB0_690
	s_lshl_b32 s2, s43, 4
	s_and_b32 s24, s2, 0x300
	s_bfe_u32 s2, s47, 0x4000b
	v_mul_hi_u32_u24_e32 v3, 0x1f00, v2
	v_mul_u32_u24_e32 v2, 0x1f00, v2
	s_and_b32 s31, s45, 0x780
	s_mul_i32 s2, s2, 0xf80000
	v_add_u32_e32 v4, s31, v182
	s_or_b32 s2, s2, s24
	s_mov_b32 s3, s25
	v_lshl_add_u64 v[2:3], v[2:3], 0, s[24:25]
	v_mov_b32_e32 v192, 0
	v_sub_u32_e32 v165, v156, v4
	v_lshl_add_u64 v[170:171], v[162:163], 0, s[2:3]
	v_add_u32_e32 v167, s31, v183
	v_subrev_u32_e32 v189, s31, v184
	v_lshl_add_u64 v[172:173], v[158:159], 0, v[2:3]
	s_mov_b32 s24, 0
	s_sub_i32 s31, 0, s30
	v_mov_b32_e32 v193, 0xf149f2ca
	s_mov_b32 s49, 2
	v_mov_b32_e32 v191, 0xf149f2ca
	v_mov_b32_e32 v190, 0
	v_mov_b32_e32 v112, 0
	v_mov_b32_e32 v113, v192
	v_mov_b32_e32 v114, v192
	v_mov_b32_e32 v115, v192
	v_mov_b32_e32 v116, 0
	v_mov_b32_e32 v117, v192
	v_mov_b32_e32 v118, v192
	v_mov_b32_e32 v119, v192
	v_mov_b32_e32 v120, 0
	v_mov_b32_e32 v121, v192
	v_mov_b32_e32 v122, v192
	v_mov_b32_e32 v123, v192
	v_mov_b32_e32 v124, 0
	v_mov_b32_e32 v125, v192
	v_mov_b32_e32 v126, v192
	v_mov_b32_e32 v127, v192
	v_mov_b32_e32 v96, 0
	v_mov_b32_e32 v97, v192
	v_mov_b32_e32 v98, v192
	v_mov_b32_e32 v99, v192
	v_mov_b32_e32 v52, 0
	v_mov_b32_e32 v53, v192
	v_mov_b32_e32 v54, v192
	v_mov_b32_e32 v55, v192
	v_mov_b32_e32 v56, 0
	v_mov_b32_e32 v57, v192
	v_mov_b32_e32 v58, v192
	v_mov_b32_e32 v59, v192
	v_mov_b32_e32 v60, 0
	v_mov_b32_e32 v61, v192
	v_mov_b32_e32 v62, v192
	v_mov_b32_e32 v63, v192
	v_mov_b32_e32 v64, 0
	v_mov_b32_e32 v65, v192
	v_mov_b32_e32 v66, v192
	v_mov_b32_e32 v67, v192
	v_mov_b32_e32 v68, 0
	v_mov_b32_e32 v69, v192
	v_mov_b32_e32 v70, v192
	v_mov_b32_e32 v71, v192
	v_mov_b32_e32 v76, 0
	v_mov_b32_e32 v77, v192
	v_mov_b32_e32 v78, v192
	v_mov_b32_e32 v79, v192
	v_mov_b32_e32 v88, 0
	v_mov_b32_e32 v89, v192
	v_mov_b32_e32 v90, v192
	v_mov_b32_e32 v91, v192
	v_mov_b32_e32 v108, 0
	v_mov_b32_e32 v109, v192
	v_mov_b32_e32 v110, v192
	v_mov_b32_e32 v111, v192
	v_mov_b32_e32 v104, 0
	v_mov_b32_e32 v105, v192
	v_mov_b32_e32 v106, v192
	v_mov_b32_e32 v107, v192
	v_mov_b32_e32 v100, 0
	v_mov_b32_e32 v101, v192
	v_mov_b32_e32 v102, v192
	v_mov_b32_e32 v103, v192
	v_mov_b32_e32 v128, 0
	v_mov_b32_e32 v129, v192
	v_mov_b32_e32 v130, v192
	v_mov_b32_e32 v131, v192
	.p2align 6
